# prologue preheader: 32 per-element 64-bit multiply address computations replaced by one base address plus running stride add
# baseline (speedup 1.0000x reference)
; __device__ __forceinline__ void tr_matrix(const float* W, int ldw, int K, int N, bf16* WT, int mode, const float* kscale, float* scr, int gw, int NGW, int lane) {
;     const int nblk = N / 32, nitems = (K / 64) * nblk;
;     float nx[32];
;     if (gw < nitems) { const int kb = gw / nblk, nb = gw % nblk;
; #pragma unroll
;         for (int i = 0; i < 32; ++i) { const int kk = 2 * i + (lane >> 5); nx[i] = W[(size_t)(64 * kb + kk) * ldw + 32 * nb + (lane & 31)]; } }
.LBB0_31:
	s_waitcnt vmcnt(2)
	v_cvt_f32_u32_e32 v33, s6
	s_lshr_b32 s48, s47, 6
	v_mov_b32_e32 v4, v2
	v_mov_b32_e32 v5, v2
	v_rcp_iflag_f32_e32 v41, v33
	v_mov_b32_e32 v6, v2
	v_mov_b32_e32 v7, v2
	v_mov_b32_e32 v8, v2
	v_mov_b32_e32 v9, v2
	v_mov_b32_e32 v10, v2
	v_mov_b32_e32 v11, v2
	v_mov_b32_e32 v12, v2
	v_mov_b32_e32 v13, v2
	v_mov_b32_e32 v14, v2
	v_mov_b32_e32 v15, v2
	v_mov_b32_e32 v16, v2
	v_mov_b32_e32 v17, v2
	v_mov_b32_e32 v18, v2
	v_mov_b32_e32 v19, v2
	v_mov_b32_e32 v20, v2
	v_mov_b32_e32 v21, v2
	v_mov_b32_e32 v22, v2
	v_mov_b32_e32 v23, v2
	v_mov_b32_e32 v24, v2
	v_mov_b32_e32 v25, v2
	v_mov_b32_e32 v26, v2
	v_mov_b32_e32 v27, v2
	v_mov_b32_e32 v28, v2
	v_mov_b32_e32 v29, v2
	v_mov_b32_e32 v30, v2
	v_mov_b32_e32 v31, v2
	v_mov_b32_e32 v32, v2
	v_mov_b32_e32 v33, v2
	s_mul_i32 s48, s48, s6
	v_mov_b32_e32 v3, v2
	s_waitcnt vmcnt(0)
	v_mov_b64_e32 v[34:35], v[32:33]
	v_cmp_gt_i32_e32 vcc, s48, v39
	v_lshlrev_b32_e32 v44, 2, v38
	v_mov_b64_e32 v[32:33], v[30:31]
	v_mov_b64_e32 v[30:31], v[28:29]
	v_mov_b64_e32 v[28:29], v[26:27]
	v_mov_b64_e32 v[26:27], v[24:25]
	v_mov_b64_e32 v[24:25], v[22:23]
	v_mov_b64_e32 v[22:23], v[20:21]
	v_mov_b64_e32 v[20:21], v[18:19]
	v_mov_b64_e32 v[18:19], v[16:17]
	v_mov_b64_e32 v[16:17], v[14:15]
	v_mov_b64_e32 v[14:15], v[12:13]
	v_mov_b64_e32 v[12:13], v[10:11]
	v_mov_b64_e32 v[10:11], v[8:9]
	v_mov_b64_e32 v[8:9], v[6:7]
	v_mov_b64_e32 v[6:7], v[4:5]
	v_mov_b64_e32 v[4:5], v[2:3]
	s_and_saveexec_b64 s[18:19], vcc
	s_cbranch_execz .LBB0_33
	v_mul_f32_e32 v3, 0x4f7ffffe, v41
	v_cvt_u32_f32_e32 v3, v3
	s_sub_i32 s4, 0, s6
	v_mov_b32_e32 v45, v2
	v_mul_lo_u32 v4, s4, v3
	v_mul_hi_u32 v4, v3, v4
	v_add_u32_e32 v3, v3, v4
	v_mul_hi_u32 v3, v42, v3
	v_mul_lo_u32 v4, v3, s6
	v_sub_u32_e32 v4, v42, v4
	v_add_u32_e32 v5, 1, v3
	v_cmp_le_u32_e64 s[4:5], s6, v4
	s_nop 1
	v_cndmask_b32_e64 v3, v3, v5, s[4:5]
	v_subrev_u32_e32 v5, s6, v4
	v_cndmask_b32_e64 v4, v4, v5, s[4:5]
	v_add_u32_e32 v5, 1, v3
	v_cmp_le_u32_e64 s[4:5], s6, v4
	s_nop 1
	v_cndmask_b32_e64 v3, v3, v5, s[4:5]
	v_xor_b32_e32 v3, v3, v84
	v_sub_u32_e32 v3, v3, v84
	v_mul_lo_u32 v4, v3, s6
	v_sub_u32_e32 v4, v39, v4
	v_lshlrev_b32_e32 v4, 5, v4
	v_lshlrev_b32_e32 v3, 6, v3
	v_ashrrev_i32_e32 v5, 31, v4
	v_or_b32_e32 v48, v3, v36
	v_lshl_add_u64 v[4:5], v[4:5], 2, s[24:25]
	v_ashrrev_i32_e32 v3, 31, v3
	v_lshl_add_u64 v[28:29], v[4:5], 0, v[44:45]
	v_mul_lo_u32 v3, s14, v3
	v_mul_lo_u32 v6, s15, v48
	v_mad_u64_u32 v[4:5], s[4:5], s14, v48, 0
	v_add3_u32 v5, v5, v3, v6
	v_lshl_add_u64 v[86:87], v[4:5], 2, v[28:29]
	s_lshl_b64 s[4:5], s[14:15], 3
	global_load_dword v4, v[86:87], off
	v_lshl_add_u64 v[86:87], s[4:5], 0, v[86:87]
	global_load_dword v5, v[86:87], off
	v_lshl_add_u64 v[86:87], s[4:5], 0, v[86:87]
	global_load_dword v6, v[86:87], off
	v_lshl_add_u64 v[86:87], s[4:5], 0, v[86:87]
	global_load_dword v7, v[86:87], off
	v_lshl_add_u64 v[86:87], s[4:5], 0, v[86:87]
	global_load_dword v8, v[86:87], off
	v_lshl_add_u64 v[86:87], s[4:5], 0, v[86:87]
	global_load_dword v9, v[86:87], off
	v_lshl_add_u64 v[86:87], s[4:5], 0, v[86:87]
	global_load_dword v10, v[86:87], off
	v_lshl_add_u64 v[86:87], s[4:5], 0, v[86:87]
	global_load_dword v11, v[86:87], off
	v_lshl_add_u64 v[86:87], s[4:5], 0, v[86:87]
	global_load_dword v12, v[86:87], off
	v_lshl_add_u64 v[86:87], s[4:5], 0, v[86:87]
	global_load_dword v13, v[86:87], off
	v_lshl_add_u64 v[86:87], s[4:5], 0, v[86:87]
	global_load_dword v14, v[86:87], off
	v_lshl_add_u64 v[86:87], s[4:5], 0, v[86:87]
	global_load_dword v15, v[86:87], off
	v_lshl_add_u64 v[86:87], s[4:5], 0, v[86:87]
	global_load_dword v16, v[86:87], off
	v_lshl_add_u64 v[86:87], s[4:5], 0, v[86:87]
	global_load_dword v17, v[86:87], off
	v_lshl_add_u64 v[86:87], s[4:5], 0, v[86:87]
	global_load_dword v18, v[86:87], off
	v_lshl_add_u64 v[86:87], s[4:5], 0, v[86:87]
	global_load_dword v19, v[86:87], off
	v_lshl_add_u64 v[86:87], s[4:5], 0, v[86:87]
	global_load_dword v20, v[86:87], off
	v_lshl_add_u64 v[86:87], s[4:5], 0, v[86:87]
	global_load_dword v21, v[86:87], off
	v_lshl_add_u64 v[86:87], s[4:5], 0, v[86:87]
	global_load_dword v22, v[86:87], off
	v_lshl_add_u64 v[86:87], s[4:5], 0, v[86:87]
	global_load_dword v23, v[86:87], off
	v_lshl_add_u64 v[86:87], s[4:5], 0, v[86:87]
	global_load_dword v24, v[86:87], off
	v_lshl_add_u64 v[86:87], s[4:5], 0, v[86:87]
	global_load_dword v25, v[86:87], off
	v_lshl_add_u64 v[86:87], s[4:5], 0, v[86:87]
	global_load_dword v26, v[86:87], off
	v_lshl_add_u64 v[86:87], s[4:5], 0, v[86:87]
	global_load_dword v27, v[86:87], off
	v_lshl_add_u64 v[86:87], s[4:5], 0, v[86:87]
	global_load_dword v28, v[86:87], off
	v_lshl_add_u64 v[86:87], s[4:5], 0, v[86:87]
	global_load_dword v29, v[86:87], off
	v_lshl_add_u64 v[86:87], s[4:5], 0, v[86:87]
	global_load_dword v30, v[86:87], off
	v_lshl_add_u64 v[86:87], s[4:5], 0, v[86:87]
	global_load_dword v31, v[86:87], off
	v_lshl_add_u64 v[86:87], s[4:5], 0, v[86:87]
	global_load_dword v32, v[86:87], off
	v_lshl_add_u64 v[86:87], s[4:5], 0, v[86:87]
	global_load_dword v33, v[86:87], off
	v_lshl_add_u64 v[86:87], s[4:5], 0, v[86:87]
	global_load_dword v34, v[86:87], off
	v_lshl_add_u64 v[86:87], s[4:5], 0, v[86:87]
	global_load_dword v35, v[86:87], off
